# hand-written MIXADD epilogue: first half's loads up front, second half's loads issued into freed registers, counted waits per group
# speedup vs baseline: 1.0059x; 1.0059x over previous
.LBB0_176:
	v_lshlrev_b32_e32 v196, 1, v146
	v_lshl_add_u32 v228, v180, 12, v196
	v_mov_b32_e32 v229, 0
	v_lshl_add_u32 v230, v180, 11, v196
	v_mov_b32_e32 v231, 0
	v_lshl_add_u64 v[228:229], s[64:65], 0, v[228:229]
	v_lshl_add_u64 v[230:231], s[18:19], 0, v[230:231]
	v_mov_b64_e32 v[252:253], v[230:231]
	s_mov_b64 s[56:57], 0x10000
	s_mov_b64 s[38:39], 0x50000
	s_mov_b64 s[44:45], 0x8000
	s_mov_b64 s[74:75], 0x28000
	global_load_dwordx4 v[130:133], v[228:229], off
	global_load_dwordx4 v[180:183], v[230:231], off
	global_load_dwordx4 v[134:137], v[228:229], off offset:256
	global_load_dwordx4 v[184:187], v[230:231], off offset:256
	v_lshl_add_u64 v[228:229], v[228:229], 0, s[56:57]
	v_lshl_add_u64 v[230:231], v[230:231], 0, s[44:45]
	global_load_dwordx4 v[138:141], v[228:229], off
	global_load_dwordx4 v[188:191], v[230:231], off
	global_load_dwordx4 v[142:145], v[228:229], off offset:256
	global_load_dwordx4 v[192:195], v[230:231], off offset:256
	v_lshl_add_u64 v[228:229], v[228:229], 0, s[56:57]
	v_lshl_add_u64 v[230:231], v[230:231], 0, s[44:45]
	global_load_dwordx4 v[146:149], v[228:229], off
	global_load_dwordx4 v[196:199], v[230:231], off
	global_load_dwordx4 v[150:153], v[228:229], off offset:256
	global_load_dwordx4 v[200:203], v[230:231], off offset:256
	v_lshl_add_u64 v[228:229], v[228:229], 0, s[56:57]
	v_lshl_add_u64 v[230:231], v[230:231], 0, s[44:45]
	global_load_dwordx4 v[154:157], v[228:229], off
	global_load_dwordx4 v[204:207], v[230:231], off
	global_load_dwordx4 v[158:161], v[228:229], off offset:256
	global_load_dwordx4 v[208:211], v[230:231], off offset:256
	v_lshl_add_u64 v[228:229], v[228:229], 0, s[38:39]
	v_lshl_add_u64 v[230:231], v[230:231], 0, s[74:75]
	s_waitcnt vmcnt(14)
	v_lshlrev_b32_e32 v212, 16, v130
	v_and_b32_e32 v213, 0xffff0000, v130
	v_lshlrev_b32_e32 v214, 16, v131
	v_and_b32_e32 v215, 0xffff0000, v131
	v_lshlrev_b32_e32 v216, 16, v132
	v_and_b32_e32 v217, 0xffff0000, v132
	v_lshlrev_b32_e32 v218, 16, v133
	v_and_b32_e32 v219, 0xffff0000, v133
	v_lshlrev_b32_e32 v220, 16, v180
	v_and_b32_e32 v221, 0xffff0000, v180
	v_lshlrev_b32_e32 v222, 16, v181
	v_and_b32_e32 v223, 0xffff0000, v181
	v_lshlrev_b32_e32 v224, 16, v182
	v_and_b32_e32 v225, 0xffff0000, v182
	v_lshlrev_b32_e32 v226, 16, v183
	v_and_b32_e32 v227, 0xffff0000, v183
	v_pk_fma_f32 v[126:127], v[212:213], v[126:127], v[220:221]
	v_pk_fma_f32 v[128:129], v[214:215], v[128:129], v[222:223]
	v_pk_fma_f32 v[122:123], v[216:217], v[122:123], v[224:225]
	v_pk_fma_f32 v[124:125], v[218:219], v[124:125], v[226:227]
	v_cvt_pk_bf16_f32 v244, v126, v127
	v_cvt_pk_bf16_f32 v245, v128, v129
	v_cvt_pk_bf16_f32 v246, v122, v123
	v_cvt_pk_bf16_f32 v247, v124, v125
	global_store_dwordx4 v[252:253], v[244:247], off
	global_load_dwordx4 v[130:133], v[228:229], off
	global_load_dwordx4 v[180:183], v[230:231], off
	s_waitcnt vmcnt(15)
	v_lshlrev_b32_e32 v212, 16, v134
	v_and_b32_e32 v213, 0xffff0000, v134
	v_lshlrev_b32_e32 v214, 16, v135
	v_and_b32_e32 v215, 0xffff0000, v135
	v_lshlrev_b32_e32 v216, 16, v136
	v_and_b32_e32 v217, 0xffff0000, v136
	v_lshlrev_b32_e32 v218, 16, v137
	v_and_b32_e32 v219, 0xffff0000, v137
	v_lshlrev_b32_e32 v220, 16, v184
	v_and_b32_e32 v221, 0xffff0000, v184
	v_lshlrev_b32_e32 v222, 16, v185
	v_and_b32_e32 v223, 0xffff0000, v185
	v_lshlrev_b32_e32 v224, 16, v186
	v_and_b32_e32 v225, 0xffff0000, v186
	v_lshlrev_b32_e32 v226, 16, v187
	v_and_b32_e32 v227, 0xffff0000, v187
	v_pk_fma_f32 v[118:119], v[212:213], v[118:119], v[220:221]
	v_pk_fma_f32 v[120:121], v[214:215], v[120:121], v[222:223]
	v_pk_fma_f32 v[114:115], v[216:217], v[114:115], v[224:225]
	v_pk_fma_f32 v[116:117], v[218:219], v[116:117], v[226:227]
	v_cvt_pk_bf16_f32 v248, v118, v119
	v_cvt_pk_bf16_f32 v249, v120, v121
	v_cvt_pk_bf16_f32 v250, v114, v115
	v_cvt_pk_bf16_f32 v251, v116, v117
	global_store_dwordx4 v[252:253], v[248:251], off offset:256
	v_lshl_add_u64 v[252:253], v[252:253], 0, s[44:45]
	global_load_dwordx4 v[134:137], v[228:229], off offset:256
	global_load_dwordx4 v[184:187], v[230:231], off offset:256
	v_lshl_add_u64 v[228:229], v[228:229], 0, s[56:57]
	v_lshl_add_u64 v[230:231], v[230:231], 0, s[44:45]
	s_waitcnt vmcnt(16)
	v_lshlrev_b32_e32 v212, 16, v138
	v_and_b32_e32 v213, 0xffff0000, v138
	v_lshlrev_b32_e32 v214, 16, v139
	v_and_b32_e32 v215, 0xffff0000, v139
	v_lshlrev_b32_e32 v216, 16, v140
	v_and_b32_e32 v217, 0xffff0000, v140
	v_lshlrev_b32_e32 v218, 16, v141
	v_and_b32_e32 v219, 0xffff0000, v141
	v_lshlrev_b32_e32 v220, 16, v188
	v_and_b32_e32 v221, 0xffff0000, v188
	v_lshlrev_b32_e32 v222, 16, v189
	v_and_b32_e32 v223, 0xffff0000, v189
	v_lshlrev_b32_e32 v224, 16, v190
	v_and_b32_e32 v225, 0xffff0000, v190
	v_lshlrev_b32_e32 v226, 16, v191
	v_and_b32_e32 v227, 0xffff0000, v191
	v_pk_fma_f32 v[110:111], v[212:213], v[110:111], v[220:221]
	v_pk_fma_f32 v[112:113], v[214:215], v[112:113], v[222:223]
	v_pk_fma_f32 v[106:107], v[216:217], v[106:107], v[224:225]
	v_pk_fma_f32 v[108:109], v[218:219], v[108:109], v[226:227]
	v_cvt_pk_bf16_f32 v244, v110, v111
	v_cvt_pk_bf16_f32 v245, v112, v113
	v_cvt_pk_bf16_f32 v246, v106, v107
	v_cvt_pk_bf16_f32 v247, v108, v109
	global_store_dwordx4 v[252:253], v[244:247], off
	global_load_dwordx4 v[138:141], v[228:229], off
	global_load_dwordx4 v[188:191], v[230:231], off
	s_waitcnt vmcnt(17)
	v_lshlrev_b32_e32 v212, 16, v142
	v_and_b32_e32 v213, 0xffff0000, v142
	v_lshlrev_b32_e32 v214, 16, v143
	v_and_b32_e32 v215, 0xffff0000, v143
	v_lshlrev_b32_e32 v216, 16, v144
	v_and_b32_e32 v217, 0xffff0000, v144
	v_lshlrev_b32_e32 v218, 16, v145
	v_and_b32_e32 v219, 0xffff0000, v145
	v_lshlrev_b32_e32 v220, 16, v192
	v_and_b32_e32 v221, 0xffff0000, v192
	v_lshlrev_b32_e32 v222, 16, v193
	v_and_b32_e32 v223, 0xffff0000, v193
	v_lshlrev_b32_e32 v224, 16, v194
	v_and_b32_e32 v225, 0xffff0000, v194
	v_lshlrev_b32_e32 v226, 16, v195
	v_and_b32_e32 v227, 0xffff0000, v195
	v_pk_fma_f32 v[102:103], v[212:213], v[102:103], v[220:221]
	v_pk_fma_f32 v[104:105], v[214:215], v[104:105], v[222:223]
	v_pk_fma_f32 v[98:99], v[216:217], v[98:99], v[224:225]
	v_pk_fma_f32 v[100:101], v[218:219], v[100:101], v[226:227]
	v_cvt_pk_bf16_f32 v248, v102, v103
	v_cvt_pk_bf16_f32 v249, v104, v105
	v_cvt_pk_bf16_f32 v250, v98, v99
	v_cvt_pk_bf16_f32 v251, v100, v101
	global_store_dwordx4 v[252:253], v[248:251], off offset:256
	v_lshl_add_u64 v[252:253], v[252:253], 0, s[44:45]
	global_load_dwordx4 v[142:145], v[228:229], off offset:256
	global_load_dwordx4 v[192:195], v[230:231], off offset:256
	v_lshl_add_u64 v[228:229], v[228:229], 0, s[56:57]
	v_lshl_add_u64 v[230:231], v[230:231], 0, s[44:45]
	s_waitcnt vmcnt(18)
	v_lshlrev_b32_e32 v212, 16, v146
	v_and_b32_e32 v213, 0xffff0000, v146
	v_lshlrev_b32_e32 v214, 16, v147
	v_and_b32_e32 v215, 0xffff0000, v147
	v_lshlrev_b32_e32 v216, 16, v148
	v_and_b32_e32 v217, 0xffff0000, v148
	v_lshlrev_b32_e32 v218, 16, v149
	v_and_b32_e32 v219, 0xffff0000, v149
	v_lshlrev_b32_e32 v220, 16, v196
	v_and_b32_e32 v221, 0xffff0000, v196
	v_lshlrev_b32_e32 v222, 16, v197
	v_and_b32_e32 v223, 0xffff0000, v197
	v_lshlrev_b32_e32 v224, 16, v198
	v_and_b32_e32 v225, 0xffff0000, v198
	v_lshlrev_b32_e32 v226, 16, v199
	v_and_b32_e32 v227, 0xffff0000, v199
	v_pk_fma_f32 v[94:95], v[212:213], v[94:95], v[220:221]
	v_pk_fma_f32 v[96:97], v[214:215], v[96:97], v[222:223]
	v_pk_fma_f32 v[90:91], v[216:217], v[90:91], v[224:225]
	v_pk_fma_f32 v[92:93], v[218:219], v[92:93], v[226:227]
	v_cvt_pk_bf16_f32 v244, v94, v95
	v_cvt_pk_bf16_f32 v245, v96, v97
	v_cvt_pk_bf16_f32 v246, v90, v91
	v_cvt_pk_bf16_f32 v247, v92, v93
	global_store_dwordx4 v[252:253], v[244:247], off
	global_load_dwordx4 v[146:149], v[228:229], off
	global_load_dwordx4 v[196:199], v[230:231], off
	s_waitcnt vmcnt(19)
	v_lshlrev_b32_e32 v212, 16, v150
	v_and_b32_e32 v213, 0xffff0000, v150
	v_lshlrev_b32_e32 v214, 16, v151
	v_and_b32_e32 v215, 0xffff0000, v151
	v_lshlrev_b32_e32 v216, 16, v152
	v_and_b32_e32 v217, 0xffff0000, v152
	v_lshlrev_b32_e32 v218, 16, v153
	v_and_b32_e32 v219, 0xffff0000, v153
	v_lshlrev_b32_e32 v220, 16, v200
	v_and_b32_e32 v221, 0xffff0000, v200
	v_lshlrev_b32_e32 v222, 16, v201
	v_and_b32_e32 v223, 0xffff0000, v201
	v_lshlrev_b32_e32 v224, 16, v202
	v_and_b32_e32 v225, 0xffff0000, v202
	v_lshlrev_b32_e32 v226, 16, v203
	v_and_b32_e32 v227, 0xffff0000, v203
	v_pk_fma_f32 v[86:87], v[212:213], v[86:87], v[220:221]
	v_pk_fma_f32 v[88:89], v[214:215], v[88:89], v[222:223]
	v_pk_fma_f32 v[82:83], v[216:217], v[82:83], v[224:225]
	v_pk_fma_f32 v[84:85], v[218:219], v[84:85], v[226:227]
	v_cvt_pk_bf16_f32 v248, v86, v87
	v_cvt_pk_bf16_f32 v249, v88, v89
	v_cvt_pk_bf16_f32 v250, v82, v83
	v_cvt_pk_bf16_f32 v251, v84, v85
	global_store_dwordx4 v[252:253], v[248:251], off offset:256
	v_lshl_add_u64 v[252:253], v[252:253], 0, s[44:45]
	global_load_dwordx4 v[150:153], v[228:229], off offset:256
	global_load_dwordx4 v[200:203], v[230:231], off offset:256
	v_lshl_add_u64 v[228:229], v[228:229], 0, s[56:57]
	v_lshl_add_u64 v[230:231], v[230:231], 0, s[44:45]
	s_waitcnt vmcnt(20)
	v_lshlrev_b32_e32 v212, 16, v154
	v_and_b32_e32 v213, 0xffff0000, v154
	v_lshlrev_b32_e32 v214, 16, v155
	v_and_b32_e32 v215, 0xffff0000, v155
	v_lshlrev_b32_e32 v216, 16, v156
	v_and_b32_e32 v217, 0xffff0000, v156
	v_lshlrev_b32_e32 v218, 16, v157
	v_and_b32_e32 v219, 0xffff0000, v157
	v_lshlrev_b32_e32 v220, 16, v204
	v_and_b32_e32 v221, 0xffff0000, v204
	v_lshlrev_b32_e32 v222, 16, v205
	v_and_b32_e32 v223, 0xffff0000, v205
	v_lshlrev_b32_e32 v224, 16, v206
	v_and_b32_e32 v225, 0xffff0000, v206
	v_lshlrev_b32_e32 v226, 16, v207
	v_and_b32_e32 v227, 0xffff0000, v207
	v_pk_fma_f32 v[78:79], v[212:213], v[78:79], v[220:221]
	v_pk_fma_f32 v[80:81], v[214:215], v[80:81], v[222:223]
	v_pk_fma_f32 v[74:75], v[216:217], v[74:75], v[224:225]
	v_pk_fma_f32 v[76:77], v[218:219], v[76:77], v[226:227]
	v_cvt_pk_bf16_f32 v244, v78, v79
	v_cvt_pk_bf16_f32 v245, v80, v81
	v_cvt_pk_bf16_f32 v246, v74, v75
	v_cvt_pk_bf16_f32 v247, v76, v77
	global_store_dwordx4 v[252:253], v[244:247], off
	global_load_dwordx4 v[154:157], v[228:229], off
	global_load_dwordx4 v[204:207], v[230:231], off
	s_waitcnt vmcnt(21)
	v_lshlrev_b32_e32 v212, 16, v158
	v_and_b32_e32 v213, 0xffff0000, v158
	v_lshlrev_b32_e32 v214, 16, v159
	v_and_b32_e32 v215, 0xffff0000, v159
	v_lshlrev_b32_e32 v216, 16, v160
	v_and_b32_e32 v217, 0xffff0000, v160
	v_lshlrev_b32_e32 v218, 16, v161
	v_and_b32_e32 v219, 0xffff0000, v161
	v_lshlrev_b32_e32 v220, 16, v208
	v_and_b32_e32 v221, 0xffff0000, v208
	v_lshlrev_b32_e32 v222, 16, v209
	v_and_b32_e32 v223, 0xffff0000, v209
	v_lshlrev_b32_e32 v224, 16, v210
	v_and_b32_e32 v225, 0xffff0000, v210
	v_lshlrev_b32_e32 v226, 16, v211
	v_and_b32_e32 v227, 0xffff0000, v211
	v_pk_fma_f32 v[70:71], v[212:213], v[70:71], v[220:221]
	v_pk_fma_f32 v[72:73], v[214:215], v[72:73], v[222:223]
	v_pk_fma_f32 v[66:67], v[216:217], v[66:67], v[224:225]
	v_pk_fma_f32 v[68:69], v[218:219], v[68:69], v[226:227]
	v_cvt_pk_bf16_f32 v248, v70, v71
	v_cvt_pk_bf16_f32 v249, v72, v73
	v_cvt_pk_bf16_f32 v250, v66, v67
	v_cvt_pk_bf16_f32 v251, v68, v69
	global_store_dwordx4 v[252:253], v[248:251], off offset:256
	v_lshl_add_u64 v[252:253], v[252:253], 0, s[74:75]
	global_load_dwordx4 v[158:161], v[228:229], off offset:256
	global_load_dwordx4 v[208:211], v[230:231], off offset:256
	s_waitcnt vmcnt(21)
	v_lshlrev_b32_e32 v212, 16, v130
	v_and_b32_e32 v213, 0xffff0000, v130
	v_lshlrev_b32_e32 v214, 16, v131
	v_and_b32_e32 v215, 0xffff0000, v131
	v_lshlrev_b32_e32 v216, 16, v132
	v_and_b32_e32 v217, 0xffff0000, v132
	v_lshlrev_b32_e32 v218, 16, v133
	v_and_b32_e32 v219, 0xffff0000, v133
	v_lshlrev_b32_e32 v220, 16, v180
	v_and_b32_e32 v221, 0xffff0000, v180
	v_lshlrev_b32_e32 v222, 16, v181
	v_and_b32_e32 v223, 0xffff0000, v181
	v_lshlrev_b32_e32 v224, 16, v182
	v_and_b32_e32 v225, 0xffff0000, v182
	v_lshlrev_b32_e32 v226, 16, v183
	v_and_b32_e32 v227, 0xffff0000, v183
	v_pk_fma_f32 v[62:63], v[212:213], v[62:63], v[220:221]
	v_pk_fma_f32 v[64:65], v[214:215], v[64:65], v[222:223]
	v_pk_fma_f32 v[58:59], v[216:217], v[58:59], v[224:225]
	v_pk_fma_f32 v[60:61], v[218:219], v[60:61], v[226:227]
	v_cvt_pk_bf16_f32 v244, v62, v63
	v_cvt_pk_bf16_f32 v245, v64, v65
	v_cvt_pk_bf16_f32 v246, v58, v59
	v_cvt_pk_bf16_f32 v247, v60, v61
	global_store_dwordx4 v[252:253], v[244:247], off
	s_waitcnt vmcnt(19)
	v_lshlrev_b32_e32 v212, 16, v134
	v_and_b32_e32 v213, 0xffff0000, v134
	v_lshlrev_b32_e32 v214, 16, v135
	v_and_b32_e32 v215, 0xffff0000, v135
	v_lshlrev_b32_e32 v216, 16, v136
	v_and_b32_e32 v217, 0xffff0000, v136
	v_lshlrev_b32_e32 v218, 16, v137
	v_and_b32_e32 v219, 0xffff0000, v137
	v_lshlrev_b32_e32 v220, 16, v184
	v_and_b32_e32 v221, 0xffff0000, v184
	v_lshlrev_b32_e32 v222, 16, v185
	v_and_b32_e32 v223, 0xffff0000, v185
	v_lshlrev_b32_e32 v224, 16, v186
	v_and_b32_e32 v225, 0xffff0000, v186
	v_lshlrev_b32_e32 v226, 16, v187
	v_and_b32_e32 v227, 0xffff0000, v187
	v_pk_fma_f32 v[54:55], v[212:213], v[54:55], v[220:221]
	v_pk_fma_f32 v[56:57], v[214:215], v[56:57], v[222:223]
	v_pk_fma_f32 v[50:51], v[216:217], v[50:51], v[224:225]
	v_pk_fma_f32 v[52:53], v[218:219], v[52:53], v[226:227]
	v_cvt_pk_bf16_f32 v248, v54, v55
	v_cvt_pk_bf16_f32 v249, v56, v57
	v_cvt_pk_bf16_f32 v250, v50, v51
	v_cvt_pk_bf16_f32 v251, v52, v53
	global_store_dwordx4 v[252:253], v[248:251], off offset:256
	v_lshl_add_u64 v[252:253], v[252:253], 0, s[44:45]
	s_waitcnt vmcnt(17)
	v_lshlrev_b32_e32 v212, 16, v138
	v_and_b32_e32 v213, 0xffff0000, v138
	v_lshlrev_b32_e32 v214, 16, v139
	v_and_b32_e32 v215, 0xffff0000, v139
	v_lshlrev_b32_e32 v216, 16, v140
	v_and_b32_e32 v217, 0xffff0000, v140
	v_lshlrev_b32_e32 v218, 16, v141
	v_and_b32_e32 v219, 0xffff0000, v141
	v_lshlrev_b32_e32 v220, 16, v188
	v_and_b32_e32 v221, 0xffff0000, v188
	v_lshlrev_b32_e32 v222, 16, v189
	v_and_b32_e32 v223, 0xffff0000, v189
	v_lshlrev_b32_e32 v224, 16, v190
	v_and_b32_e32 v225, 0xffff0000, v190
	v_lshlrev_b32_e32 v226, 16, v191
	v_and_b32_e32 v227, 0xffff0000, v191
	v_pk_fma_f32 v[46:47], v[212:213], v[46:47], v[220:221]
	v_pk_fma_f32 v[48:49], v[214:215], v[48:49], v[222:223]
	v_pk_fma_f32 v[42:43], v[216:217], v[42:43], v[224:225]
	v_pk_fma_f32 v[44:45], v[218:219], v[44:45], v[226:227]
	v_cvt_pk_bf16_f32 v244, v46, v47
	v_cvt_pk_bf16_f32 v245, v48, v49
	v_cvt_pk_bf16_f32 v246, v42, v43
	v_cvt_pk_bf16_f32 v247, v44, v45
	global_store_dwordx4 v[252:253], v[244:247], off
	s_waitcnt vmcnt(15)
	v_lshlrev_b32_e32 v212, 16, v142
	v_and_b32_e32 v213, 0xffff0000, v142
	v_lshlrev_b32_e32 v214, 16, v143
	v_and_b32_e32 v215, 0xffff0000, v143
	v_lshlrev_b32_e32 v216, 16, v144
	v_and_b32_e32 v217, 0xffff0000, v144
	v_lshlrev_b32_e32 v218, 16, v145
	v_and_b32_e32 v219, 0xffff0000, v145
	v_lshlrev_b32_e32 v220, 16, v192
	v_and_b32_e32 v221, 0xffff0000, v192
	v_lshlrev_b32_e32 v222, 16, v193
	v_and_b32_e32 v223, 0xffff0000, v193
	v_lshlrev_b32_e32 v224, 16, v194
	v_and_b32_e32 v225, 0xffff0000, v194
	v_lshlrev_b32_e32 v226, 16, v195
	v_and_b32_e32 v227, 0xffff0000, v195
	v_pk_fma_f32 v[38:39], v[212:213], v[38:39], v[220:221]
	v_pk_fma_f32 v[40:41], v[214:215], v[40:41], v[222:223]
	v_pk_fma_f32 v[34:35], v[216:217], v[34:35], v[224:225]
	v_pk_fma_f32 v[36:37], v[218:219], v[36:37], v[226:227]
	v_cvt_pk_bf16_f32 v248, v38, v39
	v_cvt_pk_bf16_f32 v249, v40, v41
	v_cvt_pk_bf16_f32 v250, v34, v35
	v_cvt_pk_bf16_f32 v251, v36, v37
	global_store_dwordx4 v[252:253], v[248:251], off offset:256
	v_lshl_add_u64 v[252:253], v[252:253], 0, s[44:45]
	s_waitcnt vmcnt(13)
	v_lshlrev_b32_e32 v212, 16, v146
	v_and_b32_e32 v213, 0xffff0000, v146
	v_lshlrev_b32_e32 v214, 16, v147
	v_and_b32_e32 v215, 0xffff0000, v147
	v_lshlrev_b32_e32 v216, 16, v148
	v_and_b32_e32 v217, 0xffff0000, v148
	v_lshlrev_b32_e32 v218, 16, v149
	v_and_b32_e32 v219, 0xffff0000, v149
	v_lshlrev_b32_e32 v220, 16, v196
	v_and_b32_e32 v221, 0xffff0000, v196
	v_lshlrev_b32_e32 v222, 16, v197
	v_and_b32_e32 v223, 0xffff0000, v197
	v_lshlrev_b32_e32 v224, 16, v198
	v_and_b32_e32 v225, 0xffff0000, v198
	v_lshlrev_b32_e32 v226, 16, v199
	v_and_b32_e32 v227, 0xffff0000, v199
	v_pk_fma_f32 v[30:31], v[212:213], v[30:31], v[220:221]
	v_pk_fma_f32 v[32:33], v[214:215], v[32:33], v[222:223]
	v_pk_fma_f32 v[26:27], v[216:217], v[26:27], v[224:225]
	v_pk_fma_f32 v[28:29], v[218:219], v[28:29], v[226:227]
	v_cvt_pk_bf16_f32 v244, v30, v31
	v_cvt_pk_bf16_f32 v245, v32, v33
	v_cvt_pk_bf16_f32 v246, v26, v27
	v_cvt_pk_bf16_f32 v247, v28, v29
	global_store_dwordx4 v[252:253], v[244:247], off
	s_waitcnt vmcnt(11)
	v_lshlrev_b32_e32 v212, 16, v150
	v_and_b32_e32 v213, 0xffff0000, v150
	v_lshlrev_b32_e32 v214, 16, v151
	v_and_b32_e32 v215, 0xffff0000, v151
	v_lshlrev_b32_e32 v216, 16, v152
	v_and_b32_e32 v217, 0xffff0000, v152
	v_lshlrev_b32_e32 v218, 16, v153
	v_and_b32_e32 v219, 0xffff0000, v153
	v_lshlrev_b32_e32 v220, 16, v200
	v_and_b32_e32 v221, 0xffff0000, v200
	v_lshlrev_b32_e32 v222, 16, v201
	v_and_b32_e32 v223, 0xffff0000, v201
	v_lshlrev_b32_e32 v224, 16, v202
	v_and_b32_e32 v225, 0xffff0000, v202
	v_lshlrev_b32_e32 v226, 16, v203
	v_and_b32_e32 v227, 0xffff0000, v203
	v_pk_fma_f32 v[22:23], v[212:213], v[22:23], v[220:221]
	v_pk_fma_f32 v[24:25], v[214:215], v[24:25], v[222:223]
	v_pk_fma_f32 v[18:19], v[216:217], v[18:19], v[224:225]
	v_pk_fma_f32 v[20:21], v[218:219], v[20:21], v[226:227]
	v_cvt_pk_bf16_f32 v248, v22, v23
	v_cvt_pk_bf16_f32 v249, v24, v25
	v_cvt_pk_bf16_f32 v250, v18, v19
	v_cvt_pk_bf16_f32 v251, v20, v21
	global_store_dwordx4 v[252:253], v[248:251], off offset:256
	v_lshl_add_u64 v[252:253], v[252:253], 0, s[44:45]
	s_waitcnt vmcnt(9)
	v_lshlrev_b32_e32 v212, 16, v154
	v_and_b32_e32 v213, 0xffff0000, v154
	v_lshlrev_b32_e32 v214, 16, v155
	v_and_b32_e32 v215, 0xffff0000, v155
	v_lshlrev_b32_e32 v216, 16, v156
	v_and_b32_e32 v217, 0xffff0000, v156
	v_lshlrev_b32_e32 v218, 16, v157
	v_and_b32_e32 v219, 0xffff0000, v157
	v_lshlrev_b32_e32 v220, 16, v204
	v_and_b32_e32 v221, 0xffff0000, v204
	v_lshlrev_b32_e32 v222, 16, v205
	v_and_b32_e32 v223, 0xffff0000, v205
	v_lshlrev_b32_e32 v224, 16, v206
	v_and_b32_e32 v225, 0xffff0000, v206
	v_lshlrev_b32_e32 v226, 16, v207
	v_and_b32_e32 v227, 0xffff0000, v207
	v_pk_fma_f32 v[14:15], v[212:213], v[14:15], v[220:221]
	v_pk_fma_f32 v[16:17], v[214:215], v[16:17], v[222:223]
	v_pk_fma_f32 v[10:11], v[216:217], v[10:11], v[224:225]
	v_pk_fma_f32 v[12:13], v[218:219], v[12:13], v[226:227]
	v_cvt_pk_bf16_f32 v244, v14, v15
	v_cvt_pk_bf16_f32 v245, v16, v17
	v_cvt_pk_bf16_f32 v246, v10, v11
	v_cvt_pk_bf16_f32 v247, v12, v13
	global_store_dwordx4 v[252:253], v[244:247], off
	s_waitcnt vmcnt(7)
	v_lshlrev_b32_e32 v212, 16, v158
	v_and_b32_e32 v213, 0xffff0000, v158
	v_lshlrev_b32_e32 v214, 16, v159
	v_and_b32_e32 v215, 0xffff0000, v159
	v_lshlrev_b32_e32 v216, 16, v160
	v_and_b32_e32 v217, 0xffff0000, v160
	v_lshlrev_b32_e32 v218, 16, v161
	v_and_b32_e32 v219, 0xffff0000, v161
	v_lshlrev_b32_e32 v220, 16, v208
	v_and_b32_e32 v221, 0xffff0000, v208
	v_lshlrev_b32_e32 v222, 16, v209
	v_and_b32_e32 v223, 0xffff0000, v209
	v_lshlrev_b32_e32 v224, 16, v210
	v_and_b32_e32 v225, 0xffff0000, v210
	v_lshlrev_b32_e32 v226, 16, v211
	v_and_b32_e32 v227, 0xffff0000, v211
	v_pk_fma_f32 v[6:7], v[212:213], v[6:7], v[220:221]
	v_pk_fma_f32 v[8:9], v[214:215], v[8:9], v[222:223]
	v_pk_fma_f32 v[2:3], v[216:217], v[2:3], v[224:225]
	v_pk_fma_f32 v[4:5], v[218:219], v[4:5], v[226:227]
	v_cvt_pk_bf16_f32 v248, v6, v7
	v_cvt_pk_bf16_f32 v249, v8, v9
	v_cvt_pk_bf16_f32 v250, v2, v3
	v_cvt_pk_bf16_f32 v251, v4, v5
	global_store_dwordx4 v[252:253], v[248:251], off offset:256
